# MLA: next-tile LDS copy placed behind the second block's QK MFMA chain (P*V chain uninterrupted) instead of inside the P*V chain
# baseline (speedup 1.0000x reference)
; #define LAS __attribute__((address_space(3)))
; DI float xhalf_max(float m) { auto rr = __builtin_amdgcn_permlane32_swap(__float_as_uint(m), __float_as_uint(m), false, false); return __builtin_fmaxf(__uint_as_float(rr[0]), __uint_as_float(rr[1])); }
; template <int DQK, int DV, bool CAUSAL, int KT, bool PRIO>
; DI void attn_unit(const bf16_t* Qb, int qpitch, const bf16_t* Kb, int kpitch, const bf16_t* Vtb, int vpitch, bf16_t* Ob, int opitch, int q0, int nt, LAS unsigned char* lds, float kbound, const float* qgain, const int* qpos, float qscale) {
;     ...
;     auto lstore = [&](int buf) {
; #pragma unroll
;         for (int i = 0; i < NKR; ++i) { const int c = tid + i * 512; if (NKC % 512 == 0 || c < NKC) *(LAS u32x4*)(lds + buf * KBUF + (c / KCH) * KS + (c % KCH) * 16) = kreg[i]; }
; #pragma unroll
;         for (int i = 0; i < NVR; ++i) { const int c = tid + i * 512; LAS unsigned char* p = lds + VOFF + buf * VBUF + (c / VCH) * VS + (c % VCH) * 16;
;             *(LAS u32x2*)p = (u32x2){vreg[i].x, vreg[i].y}; *(LAS u32x2*)(p + 8) = (u32x2){vreg[i].z, vreg[i].w}; }
;     };
;     ...
;                     if (!nomax) {
;                     float ra = __builtin_fmaxf(__builtin_fmaxf(s0[0], s0[1]), s1[0]), rb = __builtin_fmaxf(__builtin_fmaxf(s0[2], s0[3]), s1[1]);
;                     ra = __builtin_fmaxf(__builtin_fmaxf(ra, s1[2]), s1[3]);
; #pragma unroll
;                     for (int i = 4; i < 16; i += 4) { ra = __builtin_fmaxf(__builtin_fmaxf(ra, s0[i]), s0[i + 1]); rb = __builtin_fmaxf(__builtin_fmaxf(rb, s0[i + 2]), s0[i + 3]);
;                         ra = __builtin_fmaxf(__builtin_fmaxf(ra, s1[i]), s1[i + 1]); rb = __builtin_fmaxf(__builtin_fmaxf(rb, s1[i + 2]), s1[i + 3]); }
;                     float rm = __builtin_fmaxf(ra, rb);
;                     rm = xhalf_max(rm);
;                     if (first || __any(rm > THR)) {
.LBB0_1507:
	s_xor_b32 s100, s75, 1
	s_mul_i32 s101, s100, 0x6800
	v_add3_u32 v250, s101, v178, v179
	s_waitcnt vmcnt(0)
	ds_write_b128 v250, v[96:99]
	v_add3_u32 v251, s101, v181, v182
	s_mulk_i32 s100, 0xdc00
	ds_write_b128 v251, v[100:103]
	v_add3_u32 v250, s101, v183, v184
	s_add_i32 s101, s101, s100
	ds_write_b128 v250, v[104:107]
	v_add_u32_e32 v251, s101, v185
	v_add3_u32 v251, v251, v186, s57
	ds_write2_b64 v251, v[108:109], v[110:111] offset1:2
	v_add_u32_e32 v250, s101, v187
	v_add3_u32 v250, v250, v188, s57
	ds_write2_b64 v250, v[112:113], v[114:115] offset1:2
	s_andn2_b64 vcc, exec, s[2:3]
	s_cbranch_vccnz .LBB0_1514
	s_nop 7
	v_max_f32_e32 v14, v81, v81
	v_max_f32_e32 v15, v80, v80
	v_max_f32_e32 v14, v15, v14
	v_max3_f32 v15, v82, v83, v65
	v_max3_f32 v14, v14, v64, v66
	v_max3_f32 v14, v14, v67, v84
	v_max3_f32 v15, v15, v86, v87
	v_max3_f32 v14, v14, v85, v68
	v_max3_f32 v15, v15, v70, v71
	v_max3_f32 v14, v14, v69, v88
	v_max3_f32 v15, v15, v90, v91
	v_max3_f32 v14, v14, v89, v72
	v_max3_f32 v15, v15, v74, v75
	v_max3_f32 v14, v14, v73, v92
	v_max3_f32 v15, v15, v94, v95
	v_max3_f32 v14, v14, v93, v76
	v_max3_f32 v15, v15, v78, v79
	v_max3_f32 v14, v14, v77, v15
	v_mov_b32_e32 v15, v14
	s_nop 1
	v_permlane32_swap_b32_e32 v14, v15
	v_max_f32_e32 v15, v15, v15
	v_max_f32_e32 v14, v14, v14
	s_xor_b64 s[12:13], s[40:41], -1
	v_max_f32_e32 v14, v14, v15
	s_andn2_b64 vcc, exec, s[12:13]
	s_mov_b64 s[12:13], -1
	s_cbranch_vccnz .LBB0_1511
	v_cmp_lt_f32_e32 vcc, s58, v14
	s_cbranch_vccz .LBB0_1516
	v_max_f32_e32 v14, v14, v14
	v_max_f32_e32 v14, 0, v14

; DI unsigned pk2(float lo, float hi) { typedef float v2f __attribute__((ext_vector_type(2))); typedef __bf16 v2b __attribute__((ext_vector_type(2))); v2f v = {lo, hi}; v2b b = __builtin_convertvector(v, v2b); return __builtin_bit_cast(unsigned, b); }
; #define MFMA32(a, b, c) __builtin_amdgcn_mfma_f32_32x32x16_bf16((a), (b), (c), 0, 0, 0)
; template <int DQK, int DV, bool CAUSAL, int KT, bool PRIO>
; DI void attn_unit(const bf16_t* Qb, int qpitch, const bf16_t* Kb, int kpitch, const bf16_t* Vtb, int vpitch, bf16_t* Ob, int opitch, int q0, int nt, LAS unsigned char* lds, float kbound, const float* qgain, const int* qpos, float qscale) {
;     ...
;                     float ps = 0.f;
; #pragma unroll
;                     for (int i = 0; i < 16; ++i) { s0[i] = __builtin_amdgcn_exp2f(s0[i]); ps += s0[i]; asm volatile("" : "+v"(ps)); }
; #pragma unroll
;                     for (int i = 0; i < 16; ++i) { s1[i] = __builtin_amdgcn_exp2f(s1[i]); ps += s1[i]; asm volatile("" : "+v"(ps)); }
;                     lrun += ps;
;                     bf16x8 pf[4];
; #pragma unroll
;                     for (int sf = 0; sf < 2; ++sf) {
;                         u32x4 pw; pw.x = pk2(s0[8 * sf], s0[8 * sf + 1]); pw.y = pk2(s0[8 * sf + 2], s0[8 * sf + 3]); pw.z = pk2(s0[8 * sf + 4], s0[8 * sf + 5]); pw.w = pk2(s0[8 * sf + 6], s0[8 * sf + 7]); pf[sf] = __builtin_bit_cast(bf16x8, pw);
;                         u32x4 pv; pv.x = pk2(s1[8 * sf], s1[8 * sf + 1]); pv.y = pk2(s1[8 * sf + 2], s1[8 * sf + 3]); pv.z = pk2(s1[8 * sf + 4], s1[8 * sf + 5]); pv.w = pk2(s1[8 * sf + 6], s1[8 * sf + 7]); pf[2 + sf] = __builtin_bit_cast(bf16x8, pv);
;                     }
;                     __builtin_amdgcn_sched_barrier(0); __builtin_amdgcn_s_setprio(1); __builtin_amdgcn_sched_barrier(0);
; #pragma unroll
;                     for (int q4 = 0; q4 < 4; ++q4)
; #pragma unroll
;                         for (int d = 0; d < NDB; ++d) o[d] = MFMA32(vf[q4][d], pf[q4], o[d]);
;                     __builtin_amdgcn_sched_barrier(0); __builtin_amdgcn_s_setprio(0); __builtin_amdgcn_sched_barrier(0);
.LBB0_1514:
	s_nop 7
	v_exp_f32_e32 v14, v80
	v_exp_f32_e32 v15, v81
	v_exp_f32_e32 v80, v82
	v_exp_f32_e32 v81, v83
	v_add_f32_e32 v82, 0, v14
	v_exp_f32_e32 v83, v84
	v_add_f32_e32 v82, v15, v82
	v_exp_f32_e32 v84, v85
	v_add_f32_e32 v82, v80, v82
	v_exp_f32_e32 v85, v86
	v_add_f32_e32 v82, v81, v82
	v_exp_f32_e32 v86, v87
	v_add_f32_e32 v82, v83, v82
	v_exp_f32_e32 v87, v88
	v_add_f32_e32 v82, v84, v82
	v_exp_f32_e32 v88, v89
	v_add_f32_e32 v82, v85, v82
	v_exp_f32_e32 v89, v90
	v_add_f32_e32 v82, v86, v82
	v_exp_f32_e32 v90, v91
	v_add_f32_e32 v82, v87, v82
	v_exp_f32_e32 v91, v92
	v_add_f32_e32 v82, v88, v82
	v_exp_f32_e32 v92, v93
	v_add_f32_e32 v82, v89, v82
	v_exp_f32_e32 v93, v94
	v_add_f32_e32 v82, v90, v82
	v_exp_f32_e32 v94, v95
	v_add_f32_e32 v82, v91, v82
	v_exp_f32_e32 v95, v64
	v_add_f32_e32 v82, v92, v82
	v_exp_f32_e32 v194, v66
	v_add_f32_e32 v82, v93, v82
	v_exp_f32_e32 v195, v67
	v_add_f32_e32 v64, v94, v82
	v_exp_f32_e32 v82, v65
	v_exp_f32_e32 v197, v68
	v_add_f32_e32 v64, v95, v64
	v_exp_f32_e32 v198, v69
	v_add_f32_e32 v64, v82, v64
	v_exp_f32_e32 v199, v70
	v_add_f32_e32 v64, v194, v64
	v_exp_f32_e32 v71, v71
	v_add_f32_e32 v64, v195, v64
	v_exp_f32_e32 v200, v72
	v_add_f32_e32 v64, v197, v64
	v_exp_f32_e32 v201, v73
	v_add_f32_e32 v64, v198, v64
	v_exp_f32_e32 v202, v74
	v_add_f32_e32 v64, v199, v64
	v_exp_f32_e32 v203, v75
	v_add_f32_e32 v64, v71, v64
	v_exp_f32_e32 v204, v76
	v_add_f32_e32 v64, v200, v64
	v_exp_f32_e32 v205, v77
	v_add_f32_e32 v64, v201, v64
	v_exp_f32_e32 v206, v78
	v_add_f32_e32 v64, v202, v64
	v_exp_f32_e32 v79, v79
	v_add_f32_e32 v64, v203, v64
	v_cvt_pk_bf16_f32 v65, v80, v81
	v_add_f32_e32 v64, v204, v64
	v_cvt_pk_bf16_f32 v66, v83, v84
	v_add_f32_e32 v64, v205, v64
	v_cvt_pk_bf16_f32 v67, v85, v86
	v_add_f32_e32 v64, v206, v64
	v_cvt_pk_bf16_f32 v68, v95, v82
	v_add_f32_e32 v207, v79, v64
	v_cvt_pk_bf16_f32 v64, v14, v15
	v_cvt_pk_bf16_f32 v69, v194, v195
	v_cvt_pk_bf16_f32 v70, v197, v198
	v_cvt_pk_bf16_f32 v71, v199, v71
	v_cvt_pk_bf16_f32 v72, v87, v88
	v_cvt_pk_bf16_f32 v73, v89, v90
	v_cvt_pk_bf16_f32 v74, v91, v92
	v_cvt_pk_bf16_f32 v75, v93, v94
	v_cvt_pk_bf16_f32 v76, v200, v201
	v_cvt_pk_bf16_f32 v77, v202, v203
	v_cvt_pk_bf16_f32 v78, v204, v205
	v_cvt_pk_bf16_f32 v79, v206, v79
	s_setprio 1
	s_waitcnt lgkmcnt(0)
	v_mfma_f32_32x32x16_bf16 v[32:47], v[156:159], v[64:67], v[32:47]
	v_add_f32_e32 v0, v0, v207
	v_mfma_f32_32x32x16_bf16 v[16:31], v[152:155], v[64:67], v[16:31]
	v_mfma_f32_32x32x16_bf16 v[32:47], v[140:143], v[72:75], v[32:47]
	v_mfma_f32_32x32x16_bf16 v[16:31], v[148:151], v[72:75], v[16:31]
	v_mfma_f32_32x32x16_bf16 v[32:47], v[144:147], v[68:71], v[32:47]
	v_mfma_f32_32x32x16_bf16 v[16:31], v[10:13], v[68:71], v[16:31]
	v_mfma_f32_32x32x16_bf16 v[32:47], v[6:9], v[76:79], v[32:47]
	v_mfma_f32_32x32x16_bf16 v[16:31], v[2:5], v[76:79], v[16:31]
	s_setprio 0
	s_branch .LBB0_1493
	s_nop 0
	s_nop 0
	s_nop 0
	s_nop 0
	s_nop 0
	s_nop 0
	s_nop 0
	s_nop 0
	s_nop 0
	s_nop 0
	s_nop 0
	s_nop 0
	s_nop 0
